# v68 + layer-0 out-proj epilogue: the 32 loads of the f32 input x prefetched in three batches of 12 (were 16 dependent pairs)
# baseline (speedup 1.0000x reference)
.LBB0_197:
	v_lshl_or_b32 v154, s3, 8, v198
	s_lshr_b32 s3, s41, 4
	s_cmp_lt_i32 s41, 64
	s_mulk_i32 s3, 0x1800
	s_cselect_b32 s10, s3, 0x6000
	s_ashr_i32 s11, s10, 31
	s_lshl_b64 s[10:11], s[10:11], 2
	s_add_u32 s10, s83, s10
	s_addc_u32 s11, s85, s11
	v_ashrrev_i32_e32 v155, 31, v154
	v_lshl_add_u64 v[118:119], v[154:155], 2, s[10:11]
	global_load_dwordx4 v[122:125], v[118:119], off offset:16
	global_load_dwordx4 v[126:129], v[118:119], off
	global_load_dwordx4 v[114:117], v[118:119], off offset:528
	s_nop 0
	global_load_dwordx4 v[118:121], v[118:119], off offset:512
	v_lshl_add_u32 v150, s41, 8, v196
	v_or_b32_e32 v152, 16, v150
	v_or_b32_e32 v148, 32, v150
	v_or_b32_e32 v146, 48, v150
	s_andn2_b64 vcc, exec, s[74:75]
	v_ashrrev_i32_e32 v151, 31, v150
	v_lshlrev_b64 v[184:185], 1, v[154:155]
	v_ashrrev_i32_e32 v153, 31, v152
	v_ashrrev_i32_e32 v149, 31, v148
	v_ashrrev_i32_e32 v147, 31, v146
	s_cbranch_vccnz .LBB0_203
	s_nop 0
	s_nop 0
	s_nop 0
	v_lshlrev_b64 v[156:157], 11, v[150:151]
	v_lshl_add_u64 v[156:157], s[52:53], 0, v[156:157]
	v_lshl_add_u64 v[164:165], v[156:157], 0, v[184:185]
	v_lshlrev_b64 v[156:157], 12, v[150:151]
	v_lshl_add_u64 v[156:157], s[48:49], 0, v[156:157]
	v_lshlrev_b64 v[154:155], 2, v[154:155]
	v_lshlrev_b64 v[182:183], 12, v[150:151]
	v_lshl_add_u64 v[182:183], s[48:49], 0, v[182:183]
	v_lshl_add_u64 v[182:183], v[182:183], 0, v[154:155]
	global_load_dwordx4 v[170:173], v[182:183], off offset:16
	global_load_dwordx4 v[174:177], v[182:183], off
	global_load_dwordx4 v[178:181], v[182:183], off offset:528
	global_load_dwordx4 v[186:189], v[182:183], off offset:512
	v_lshlrev_b64 v[182:183], 12, v[152:153]
	v_lshl_add_u64 v[182:183], s[48:49], 0, v[182:183]
	v_lshl_add_u64 v[182:183], v[182:183], 0, v[154:155]
	global_load_dwordx4 v[190:193], v[182:183], off offset:16
	global_load_dwordx4 v[194:197], v[182:183], off
	global_load_dwordx4 v[198:201], v[182:183], off offset:528
	global_load_dwordx4 v[202:205], v[182:183], off offset:512
	v_lshlrev_b64 v[182:183], 12, v[148:149]
	v_lshl_add_u64 v[182:183], s[48:49], 0, v[182:183]
	v_lshl_add_u64 v[182:183], v[182:183], 0, v[154:155]
	global_load_dwordx4 v[236:239], v[182:183], off offset:16
	global_load_dwordx4 v[240:243], v[182:183], off
	global_load_dwordx4 v[244:247], v[182:183], off offset:528
	global_load_dwordx4 v[248:251], v[182:183], off offset:512
	v_lshl_add_u64 v[166:167], v[156:157], 0, v[154:155]
	s_waitcnt vmcnt(10)
	s_nop 0
	v_mov_b32_e32 v156, v170
	v_mov_b32_e32 v157, v171
	v_mov_b32_e32 v158, v172
	v_mov_b32_e32 v159, v173
	v_mov_b32_e32 v160, v174
	v_mov_b32_e32 v161, v175
	v_mov_b32_e32 v162, v176
	v_mov_b32_e32 v163, v177
	v_pk_fma_f32 v[168:169], v[140:141], v[124:125], v[158:159]
	v_pk_fma_f32 v[158:159], v[138:139], v[122:123], v[156:157]
	v_pk_fma_f32 v[162:163], v[144:145], v[128:129], v[162:163]
	v_pk_fma_f32 v[160:161], v[142:143], v[126:127], v[160:161]
	s_nop 0
	v_cvt_pk_bf16_f32 v156, v160, v161
	v_cvt_pk_bf16_f32 v157, v162, v163
	v_cvt_pk_bf16_f32 v158, v158, v159
	v_cvt_pk_bf16_f32 v159, v168, v169
	global_store_dwordx4 v[164:165], v[156:159], off
	s_waitcnt vmcnt(9)
	s_nop 0
	v_mov_b32_e32 v156, v178
	v_mov_b32_e32 v157, v179
	v_mov_b32_e32 v158, v180
	v_mov_b32_e32 v159, v181
	s_nop 0
	v_mov_b32_e32 v160, v186
	v_mov_b32_e32 v161, v187
	v_mov_b32_e32 v162, v188
	v_mov_b32_e32 v163, v189
	v_pk_fma_f32 v[166:167], v[132:133], v[116:117], v[158:159]
	v_pk_fma_f32 v[162:163], v[136:137], v[120:121], v[162:163]
	v_pk_fma_f32 v[160:161], v[134:135], v[118:119], v[160:161]
	v_pk_fma_f32 v[158:159], v[130:131], v[114:115], v[156:157]
	v_cvt_pk_bf16_f32 v156, v160, v161
	v_cvt_pk_bf16_f32 v157, v162, v163
	s_nop 0
	v_cvt_pk_bf16_f32 v158, v158, v159
	v_cvt_pk_bf16_f32 v159, v166, v167
	global_store_dwordx4 v[164:165], v[156:159], off offset:256
	s_nop 1
	v_lshlrev_b64 v[156:157], 11, v[152:153]
	v_lshl_add_u64 v[156:157], s[52:53], 0, v[156:157]
	v_lshl_add_u64 v[164:165], v[156:157], 0, v[184:185]
	v_lshlrev_b64 v[156:157], 12, v[152:153]
	v_lshl_add_u64 v[156:157], s[48:49], 0, v[156:157]
	v_lshl_add_u64 v[166:167], v[156:157], 0, v[154:155]
	s_waitcnt vmcnt(8)
	s_nop 0
	v_mov_b32_e32 v156, v190
	v_mov_b32_e32 v157, v191
	v_mov_b32_e32 v158, v192
	v_mov_b32_e32 v159, v193
	v_mov_b32_e32 v160, v194
	v_mov_b32_e32 v161, v195
	v_mov_b32_e32 v162, v196
	v_mov_b32_e32 v163, v197
	v_pk_fma_f32 v[168:169], v[108:109], v[124:125], v[158:159]
	v_pk_fma_f32 v[158:159], v[106:107], v[122:123], v[156:157]
	v_pk_fma_f32 v[162:163], v[112:113], v[128:129], v[162:163]
	v_pk_fma_f32 v[160:161], v[110:111], v[126:127], v[160:161]
	s_nop 0
	v_cvt_pk_bf16_f32 v156, v160, v161
	v_cvt_pk_bf16_f32 v157, v162, v163
	v_cvt_pk_bf16_f32 v158, v158, v159
	v_cvt_pk_bf16_f32 v159, v168, v169
	global_store_dwordx4 v[164:165], v[156:159], off
	s_waitcnt vmcnt(7)
	s_nop 0
	v_mov_b32_e32 v156, v198
	v_mov_b32_e32 v157, v199
	v_mov_b32_e32 v158, v200
	v_mov_b32_e32 v159, v201
	s_nop 0
	v_mov_b32_e32 v160, v202
	v_mov_b32_e32 v161, v203
	v_mov_b32_e32 v162, v204
	v_mov_b32_e32 v163, v205
	v_pk_fma_f32 v[166:167], v[100:101], v[116:117], v[158:159]
	v_pk_fma_f32 v[162:163], v[104:105], v[120:121], v[162:163]
	v_pk_fma_f32 v[160:161], v[102:103], v[118:119], v[160:161]
	v_pk_fma_f32 v[158:159], v[98:99], v[114:115], v[156:157]
	v_cvt_pk_bf16_f32 v156, v160, v161
	v_cvt_pk_bf16_f32 v157, v162, v163
	s_nop 0
	v_cvt_pk_bf16_f32 v158, v158, v159
	v_cvt_pk_bf16_f32 v159, v166, v167
	global_store_dwordx4 v[164:165], v[156:159], off offset:256
	s_nop 1
	v_lshlrev_b64 v[156:157], 11, v[148:149]
	v_lshl_add_u64 v[156:157], s[52:53], 0, v[156:157]
	v_lshl_add_u64 v[164:165], v[156:157], 0, v[184:185]
	v_lshlrev_b64 v[156:157], 12, v[148:149]
	v_lshl_add_u64 v[156:157], s[48:49], 0, v[156:157]
	v_lshl_add_u64 v[166:167], v[156:157], 0, v[154:155]
	s_waitcnt vmcnt(6)
	s_nop 0
	v_mov_b32_e32 v156, v236
	v_mov_b32_e32 v157, v237
	v_mov_b32_e32 v158, v238
	v_mov_b32_e32 v159, v239
	v_mov_b32_e32 v160, v240
	v_mov_b32_e32 v161, v241
	v_mov_b32_e32 v162, v242
	v_mov_b32_e32 v163, v243
	v_pk_fma_f32 v[168:169], v[92:93], v[124:125], v[158:159]
	v_pk_fma_f32 v[158:159], v[90:91], v[122:123], v[156:157]
	v_pk_fma_f32 v[162:163], v[96:97], v[128:129], v[162:163]
	v_pk_fma_f32 v[160:161], v[94:95], v[126:127], v[160:161]
	s_nop 0
	v_cvt_pk_bf16_f32 v156, v160, v161
	v_cvt_pk_bf16_f32 v157, v162, v163
	v_cvt_pk_bf16_f32 v158, v158, v159
	v_cvt_pk_bf16_f32 v159, v168, v169
	global_store_dwordx4 v[164:165], v[156:159], off
	s_waitcnt vmcnt(5)
	s_nop 0
	v_mov_b32_e32 v156, v244
	v_mov_b32_e32 v157, v245
	v_mov_b32_e32 v158, v246
	v_mov_b32_e32 v159, v247
	s_nop 0
	v_mov_b32_e32 v160, v248
	v_mov_b32_e32 v161, v249
	v_mov_b32_e32 v162, v250
	v_mov_b32_e32 v163, v251
	v_pk_fma_f32 v[166:167], v[84:85], v[116:117], v[158:159]
	v_pk_fma_f32 v[162:163], v[88:89], v[120:121], v[162:163]
	v_pk_fma_f32 v[160:161], v[86:87], v[118:119], v[160:161]
	v_pk_fma_f32 v[158:159], v[82:83], v[114:115], v[156:157]
	v_cvt_pk_bf16_f32 v156, v160, v161
	v_cvt_pk_bf16_f32 v157, v162, v163
	s_nop 0
	v_cvt_pk_bf16_f32 v158, v158, v159
	v_cvt_pk_bf16_f32 v159, v166, v167
	global_store_dwordx4 v[164:165], v[156:159], off offset:256
	s_nop 1
	v_lshlrev_b64 v[182:183], 12, v[146:147]
	v_lshl_add_u64 v[182:183], s[48:49], 0, v[182:183]
	v_lshl_add_u64 v[182:183], v[182:183], 0, v[154:155]
	global_load_dwordx4 v[170:173], v[182:183], off offset:16
	global_load_dwordx4 v[174:177], v[182:183], off
	global_load_dwordx4 v[178:181], v[182:183], off offset:528
	global_load_dwordx4 v[186:189], v[182:183], off offset:512
	v_add_u32_e32 v206, 0x80, v150
	v_ashrrev_i32_e32 v207, 31, v206
	v_lshlrev_b64 v[182:183], 12, v[206:207]
	v_lshl_add_u64 v[182:183], s[48:49], 0, v[182:183]
	v_lshl_add_u64 v[182:183], v[182:183], 0, v[154:155]
	global_load_dwordx4 v[190:193], v[182:183], off offset:16
	global_load_dwordx4 v[194:197], v[182:183], off
	global_load_dwordx4 v[198:201], v[182:183], off offset:528
	global_load_dwordx4 v[202:205], v[182:183], off offset:512
	v_add_u32_e32 v206, 0x90, v150
	v_ashrrev_i32_e32 v207, 31, v206
	v_lshlrev_b64 v[182:183], 12, v[206:207]
	v_lshl_add_u64 v[182:183], s[48:49], 0, v[182:183]
	v_lshl_add_u64 v[182:183], v[182:183], 0, v[154:155]
	global_load_dwordx4 v[236:239], v[182:183], off offset:16
	global_load_dwordx4 v[240:243], v[182:183], off
	global_load_dwordx4 v[244:247], v[182:183], off offset:528
	global_load_dwordx4 v[248:251], v[182:183], off offset:512
	v_lshlrev_b64 v[156:157], 11, v[146:147]
	v_lshl_add_u64 v[156:157], s[52:53], 0, v[156:157]
	v_lshl_add_u64 v[164:165], v[156:157], 0, v[184:185]
	v_lshlrev_b64 v[156:157], 12, v[146:147]
	v_lshl_add_u64 v[156:157], s[48:49], 0, v[156:157]
	v_lshl_add_u64 v[166:167], v[156:157], 0, v[154:155]
	s_waitcnt vmcnt(10)
	s_nop 0
	v_mov_b32_e32 v156, v170
	v_mov_b32_e32 v157, v171
	v_mov_b32_e32 v158, v172
	v_mov_b32_e32 v159, v173
	v_mov_b32_e32 v160, v174
	v_mov_b32_e32 v161, v175
	v_mov_b32_e32 v162, v176
	v_mov_b32_e32 v163, v177
	v_pk_fma_f32 v[168:169], v[76:77], v[124:125], v[158:159]
	v_pk_fma_f32 v[158:159], v[74:75], v[122:123], v[156:157]
	v_pk_fma_f32 v[162:163], v[80:81], v[128:129], v[162:163]
	v_pk_fma_f32 v[160:161], v[78:79], v[126:127], v[160:161]
	s_nop 0
	v_cvt_pk_bf16_f32 v156, v160, v161
	v_cvt_pk_bf16_f32 v157, v162, v163
	v_cvt_pk_bf16_f32 v158, v158, v159
	v_cvt_pk_bf16_f32 v159, v168, v169
	global_store_dwordx4 v[164:165], v[156:159], off
	s_waitcnt vmcnt(9)
	s_nop 0
	v_mov_b32_e32 v156, v178
	v_mov_b32_e32 v157, v179
	v_mov_b32_e32 v158, v180
	v_mov_b32_e32 v159, v181
	s_nop 0
	v_mov_b32_e32 v160, v186
	v_mov_b32_e32 v161, v187
	v_mov_b32_e32 v162, v188
	v_mov_b32_e32 v163, v189
	v_pk_fma_f32 v[166:167], v[68:69], v[116:117], v[158:159]
	v_pk_fma_f32 v[160:161], v[70:71], v[118:119], v[160:161]
	v_pk_fma_f32 v[158:159], v[66:67], v[114:115], v[156:157]
	v_cvt_pk_bf16_f32 v156, v160, v161
	v_pk_fma_f32 v[162:163], v[72:73], v[120:121], v[162:163]
	s_nop 0
	v_cvt_pk_bf16_f32 v157, v162, v163
	v_cvt_pk_bf16_f32 v158, v158, v159
	v_cvt_pk_bf16_f32 v159, v166, v167
	global_store_dwordx4 v[164:165], v[156:159], off offset:256
	s_nop 1
	v_add_u32_e32 v156, 0x80, v150
	v_ashrrev_i32_e32 v157, 31, v156
	v_lshlrev_b64 v[158:159], 11, v[156:157]
	v_lshlrev_b64 v[156:157], 12, v[156:157]
	v_lshl_add_u64 v[156:157], s[48:49], 0, v[156:157]
	v_lshl_add_u64 v[158:159], s[52:53], 0, v[158:159]
	v_lshl_add_u64 v[166:167], v[156:157], 0, v[154:155]
	v_lshl_add_u64 v[164:165], v[158:159], 0, v[184:185]
	s_waitcnt vmcnt(8)
	s_nop 0
	v_mov_b32_e32 v156, v190
	v_mov_b32_e32 v157, v191
	v_mov_b32_e32 v158, v192
	v_mov_b32_e32 v159, v193
	v_mov_b32_e32 v160, v194
	v_mov_b32_e32 v161, v195
	v_mov_b32_e32 v162, v196
	v_mov_b32_e32 v163, v197
	v_pk_fma_f32 v[168:169], v[60:61], v[124:125], v[158:159]
	v_pk_fma_f32 v[158:159], v[58:59], v[122:123], v[156:157]
	v_pk_fma_f32 v[162:163], v[64:65], v[128:129], v[162:163]
	v_pk_fma_f32 v[160:161], v[62:63], v[126:127], v[160:161]
	s_nop 0
	v_cvt_pk_bf16_f32 v156, v160, v161
	v_cvt_pk_bf16_f32 v157, v162, v163
	v_cvt_pk_bf16_f32 v158, v158, v159
	v_cvt_pk_bf16_f32 v159, v168, v169
	global_store_dwordx4 v[164:165], v[156:159], off
	s_waitcnt vmcnt(7)
	s_nop 0
	v_mov_b32_e32 v156, v198
	v_mov_b32_e32 v157, v199
	v_mov_b32_e32 v158, v200
	v_mov_b32_e32 v159, v201
	s_nop 0
	v_mov_b32_e32 v160, v202
	v_mov_b32_e32 v161, v203
	v_mov_b32_e32 v162, v204
	v_mov_b32_e32 v163, v205
	v_pk_fma_f32 v[166:167], v[52:53], v[116:117], v[158:159]
	v_pk_fma_f32 v[160:161], v[54:55], v[118:119], v[160:161]
	v_pk_fma_f32 v[158:159], v[50:51], v[114:115], v[156:157]
	v_cvt_pk_bf16_f32 v156, v160, v161
	v_pk_fma_f32 v[162:163], v[56:57], v[120:121], v[162:163]
	s_nop 0
	v_cvt_pk_bf16_f32 v157, v162, v163
	v_cvt_pk_bf16_f32 v158, v158, v159
	v_cvt_pk_bf16_f32 v159, v166, v167
	global_store_dwordx4 v[164:165], v[156:159], off offset:256
	s_nop 1
	v_add_u32_e32 v156, 0x90, v150
	v_ashrrev_i32_e32 v157, 31, v156
	v_lshlrev_b64 v[158:159], 11, v[156:157]
	v_lshlrev_b64 v[156:157], 12, v[156:157]
	v_lshl_add_u64 v[156:157], s[48:49], 0, v[156:157]
	v_lshl_add_u64 v[158:159], s[52:53], 0, v[158:159]
	v_lshl_add_u64 v[166:167], v[156:157], 0, v[154:155]
	v_lshl_add_u64 v[164:165], v[158:159], 0, v[184:185]
	s_waitcnt vmcnt(6)
	s_nop 0
	v_mov_b32_e32 v156, v236
	v_mov_b32_e32 v157, v237
	v_mov_b32_e32 v158, v238
	v_mov_b32_e32 v159, v239
	v_mov_b32_e32 v160, v240
	v_mov_b32_e32 v161, v241
	v_mov_b32_e32 v162, v242
	v_mov_b32_e32 v163, v243
	v_pk_fma_f32 v[168:169], v[44:45], v[124:125], v[158:159]
	v_pk_fma_f32 v[158:159], v[42:43], v[122:123], v[156:157]
	v_pk_fma_f32 v[162:163], v[48:49], v[128:129], v[162:163]
	v_pk_fma_f32 v[160:161], v[46:47], v[126:127], v[160:161]
	s_nop 0
	v_cvt_pk_bf16_f32 v156, v160, v161
	v_cvt_pk_bf16_f32 v157, v162, v163
	v_cvt_pk_bf16_f32 v158, v158, v159
	v_cvt_pk_bf16_f32 v159, v168, v169
	global_store_dwordx4 v[164:165], v[156:159], off
	s_waitcnt vmcnt(5)
	s_nop 0
	v_mov_b32_e32 v156, v244
	v_mov_b32_e32 v157, v245
	v_mov_b32_e32 v158, v246
	v_mov_b32_e32 v159, v247
	s_nop 0
	v_mov_b32_e32 v160, v248
	v_mov_b32_e32 v161, v249
	v_mov_b32_e32 v162, v250
	v_mov_b32_e32 v163, v251
	v_pk_fma_f32 v[166:167], v[36:37], v[116:117], v[158:159]
	v_pk_fma_f32 v[160:161], v[38:39], v[118:119], v[160:161]
	v_pk_fma_f32 v[158:159], v[34:35], v[114:115], v[156:157]
	v_cvt_pk_bf16_f32 v156, v160, v161
	v_pk_fma_f32 v[162:163], v[40:41], v[120:121], v[162:163]
	s_nop 0
	v_cvt_pk_bf16_f32 v157, v162, v163
	v_cvt_pk_bf16_f32 v158, v158, v159
	v_cvt_pk_bf16_f32 v159, v166, v167
	global_store_dwordx4 v[164:165], v[156:159], off offset:256
	s_nop 1
	v_add_u32_e32 v206, 0xa0, v150
	v_ashrrev_i32_e32 v207, 31, v206
	v_lshlrev_b64 v[182:183], 12, v[206:207]
	v_lshl_add_u64 v[182:183], s[48:49], 0, v[182:183]
	v_lshl_add_u64 v[182:183], v[182:183], 0, v[154:155]
	global_load_dwordx4 v[170:173], v[182:183], off offset:16
	global_load_dwordx4 v[174:177], v[182:183], off
	global_load_dwordx4 v[178:181], v[182:183], off offset:528
	global_load_dwordx4 v[186:189], v[182:183], off offset:512
	v_add_u32_e32 v206, 0xb0, v150
	v_ashrrev_i32_e32 v207, 31, v206
	v_lshlrev_b64 v[182:183], 12, v[206:207]
	v_lshl_add_u64 v[182:183], s[48:49], 0, v[182:183]
	v_lshl_add_u64 v[182:183], v[182:183], 0, v[154:155]
	global_load_dwordx4 v[190:193], v[182:183], off offset:16
	global_load_dwordx4 v[194:197], v[182:183], off
	global_load_dwordx4 v[198:201], v[182:183], off offset:528
	global_load_dwordx4 v[202:205], v[182:183], off offset:512
	v_add_u32_e32 v156, 0xa0, v150
	v_ashrrev_i32_e32 v157, 31, v156
	v_lshlrev_b64 v[158:159], 11, v[156:157]
	v_lshlrev_b64 v[156:157], 12, v[156:157]
	v_lshl_add_u64 v[156:157], s[48:49], 0, v[156:157]
	v_lshl_add_u64 v[158:159], s[52:53], 0, v[158:159]
	v_lshl_add_u64 v[166:167], v[156:157], 0, v[154:155]
	v_lshl_add_u64 v[164:165], v[158:159], 0, v[184:185]
	s_waitcnt vmcnt(6)
	s_nop 0
	v_mov_b32_e32 v156, v170
	v_mov_b32_e32 v157, v171
	v_mov_b32_e32 v158, v172
	v_mov_b32_e32 v159, v173
	v_mov_b32_e32 v160, v174
	v_mov_b32_e32 v161, v175
	v_mov_b32_e32 v162, v176
	v_mov_b32_e32 v163, v177
	v_pk_fma_f32 v[168:169], v[28:29], v[124:125], v[158:159]
	v_pk_fma_f32 v[158:159], v[26:27], v[122:123], v[156:157]
	v_pk_fma_f32 v[162:163], v[32:33], v[128:129], v[162:163]
	v_pk_fma_f32 v[160:161], v[30:31], v[126:127], v[160:161]
	s_nop 0
	v_cvt_pk_bf16_f32 v156, v160, v161
	v_cvt_pk_bf16_f32 v157, v162, v163
	v_cvt_pk_bf16_f32 v158, v158, v159
	v_cvt_pk_bf16_f32 v159, v168, v169
	global_store_dwordx4 v[164:165], v[156:159], off
	s_waitcnt vmcnt(5)
	s_nop 0
	v_mov_b32_e32 v156, v178
	v_mov_b32_e32 v157, v179
	v_mov_b32_e32 v158, v180
	v_mov_b32_e32 v159, v181
	s_nop 0
	v_mov_b32_e32 v160, v186
	v_mov_b32_e32 v161, v187
	v_mov_b32_e32 v162, v188
	v_mov_b32_e32 v163, v189
	v_pk_fma_f32 v[166:167], v[20:21], v[116:117], v[158:159]
	v_pk_fma_f32 v[160:161], v[22:23], v[118:119], v[160:161]
	v_pk_fma_f32 v[158:159], v[18:19], v[114:115], v[156:157]
	v_cvt_pk_bf16_f32 v156, v160, v161
	v_pk_fma_f32 v[162:163], v[24:25], v[120:121], v[162:163]
	s_nop 0
	v_cvt_pk_bf16_f32 v157, v162, v163
	v_cvt_pk_bf16_f32 v158, v158, v159
	v_cvt_pk_bf16_f32 v159, v166, v167
	global_store_dwordx4 v[164:165], v[156:159], off offset:256
	s_nop 1
	v_add_u32_e32 v156, 0xb0, v150
	v_ashrrev_i32_e32 v157, 31, v156
	v_lshlrev_b64 v[158:159], 11, v[156:157]
	v_lshlrev_b64 v[156:157], 12, v[156:157]
	v_lshl_add_u64 v[156:157], s[48:49], 0, v[156:157]
	v_lshl_add_u64 v[158:159], s[52:53], 0, v[158:159]
	v_lshl_add_u64 v[164:165], v[156:157], 0, v[154:155]
	v_lshl_add_u64 v[162:163], v[158:159], 0, v[184:185]
	s_waitcnt vmcnt(4)
	s_nop 0
	v_mov_b32_e32 v154, v190
	v_mov_b32_e32 v155, v191
	v_mov_b32_e32 v156, v192
	v_mov_b32_e32 v157, v193
	v_mov_b32_e32 v158, v194
	v_mov_b32_e32 v159, v195
	v_mov_b32_e32 v160, v196
	v_mov_b32_e32 v161, v197
	v_pk_fma_f32 v[166:167], v[12:13], v[124:125], v[156:157]
	v_pk_fma_f32 v[156:157], v[10:11], v[122:123], v[154:155]
	v_pk_fma_f32 v[160:161], v[16:17], v[128:129], v[160:161]
	v_pk_fma_f32 v[158:159], v[14:15], v[126:127], v[158:159]
	s_nop 0
	v_cvt_pk_bf16_f32 v154, v158, v159
	v_cvt_pk_bf16_f32 v155, v160, v161
	v_cvt_pk_bf16_f32 v156, v156, v157
	v_cvt_pk_bf16_f32 v157, v166, v167
	global_store_dwordx4 v[162:163], v[154:157], off
	s_waitcnt vmcnt(3)
	s_nop 0
	v_mov_b32_e32 v154, v198
	v_mov_b32_e32 v155, v199
	v_mov_b32_e32 v156, v200
	v_mov_b32_e32 v157, v201
	s_nop 0
	v_mov_b32_e32 v158, v202
	v_mov_b32_e32 v159, v203
	v_mov_b32_e32 v160, v204
	v_mov_b32_e32 v161, v205
	v_pk_fma_f32 v[164:165], v[4:5], v[116:117], v[156:157]
	v_pk_fma_f32 v[156:157], v[2:3], v[114:115], v[154:155]
	v_pk_fma_f32 v[160:161], v[8:9], v[120:121], v[160:161]
	v_pk_fma_f32 v[158:159], v[6:7], v[118:119], v[158:159]
	s_nop 0
	v_cvt_pk_bf16_f32 v154, v158, v159
	v_cvt_pk_bf16_f32 v155, v160, v161
	v_cvt_pk_bf16_f32 v156, v156, v157
	v_cvt_pk_bf16_f32 v157, v164, v165
	global_store_dwordx4 v[162:163], v[154:157], off offset:256
	s_cbranch_execnz .LBB0_200
